# K-loop heads pinned to 256-byte boundaries; hand-written gate-up epilogue; w_down streaming; hand-written idle-round quantiser
# baseline (speedup 1.0000x reference)
.LBB0_290:
	s_ashr_i32 s79, s78, 31
	s_lshl_b64 s[80:81], s[78:79], 21
	s_add_u32 s80, s22, s80
	s_addc_u32 s81, s23, s81
	s_and_b64 s[82:83], s[4:5], exec
	s_cselect_b32 s79, s81, s7
	s_cselect_b32 s88, s80, s6
	s_ashr_i32 s11, s10, 31
	s_lshl_b64 s[82:83], s[10:11], 21
	s_add_u32 s82, s8, s82
	s_addc_u32 s83, s9, s83
	s_and_b64 s[86:87], s[4:5], exec
	s_cselect_b32 s11, s83, s85
	s_cselect_b32 s89, s82, s84
	s_add_u32 s6, s6, 0x100080
	s_addc_u32 s7, s7, 0
	s_add_u32 s90, s84, 0x100
	v_mov_b32_e32 v50, 0
	s_addc_u32 s91, s85, 0
	s_mov_b32 vcc_lo, -2
	v_mov_b32_e32 v51, v50
	v_mov_b32_e32 v52, v50
	v_mov_b32_e32 v53, v50
	v_mov_b32_e32 v54, v50
	v_mov_b32_e32 v55, v50
	v_mov_b32_e32 v56, v50
	v_mov_b32_e32 v57, v50
	v_mov_b32_e32 v62, v50
	v_mov_b32_e32 v63, v50
	v_mov_b32_e32 v64, v50
	v_mov_b32_e32 v65, v50
	v_mov_b32_e32 v70, v50
	v_mov_b32_e32 v71, v50
	v_mov_b32_e32 v72, v50
	v_mov_b32_e32 v73, v50
	v_mov_b32_e32 v78, v50
	v_mov_b32_e32 v79, v50
	v_mov_b32_e32 v80, v50
	v_mov_b32_e32 v81, v50
	v_mov_b32_e32 v86, v50
	v_mov_b32_e32 v87, v50
	v_mov_b32_e32 v88, v50
	v_mov_b32_e32 v89, v50
	v_mov_b32_e32 v94, v50
	v_mov_b32_e32 v95, v50
	v_mov_b32_e32 v96, v50
	v_mov_b32_e32 v97, v50
	v_mov_b32_e32 v102, v50
	v_mov_b32_e32 v103, v50
	v_mov_b32_e32 v104, v50
	v_mov_b32_e32 v105, v50
	v_mov_b32_e32 v58, v50
	v_mov_b32_e32 v59, v50
	v_mov_b32_e32 v60, v50
	v_mov_b32_e32 v61, v50
	v_mov_b32_e32 v66, v50
	v_mov_b32_e32 v67, v50
	v_mov_b32_e32 v68, v50
	v_mov_b32_e32 v69, v50
	v_mov_b32_e32 v74, v50
	v_mov_b32_e32 v75, v50
	v_mov_b32_e32 v76, v50
	v_mov_b32_e32 v77, v50
	v_mov_b32_e32 v82, v50
	v_mov_b32_e32 v83, v50
	v_mov_b32_e32 v84, v50
	v_mov_b32_e32 v85, v50
	v_mov_b32_e32 v90, v50
	v_mov_b32_e32 v91, v50
	v_mov_b32_e32 v92, v50
	v_mov_b32_e32 v93, v50
	v_mov_b32_e32 v98, v50
	v_mov_b32_e32 v99, v50
	v_mov_b32_e32 v100, v50
	v_mov_b32_e32 v101, v50
	v_mov_b32_e32 v106, v50
	v_mov_b32_e32 v107, v50
	v_mov_b32_e32 v108, v50
	v_mov_b32_e32 v109, v50
	v_mov_b32_e32 v110, v50
	v_mov_b32_e32 v111, v50
	v_mov_b32_e32 v112, v50
	v_mov_b32_e32 v113, v50
	v_mov_b32_e32 v114, v50
	v_mov_b32_e32 v115, v50
	v_mov_b32_e32 v116, v50
	v_mov_b32_e32 v117, v50
	v_mov_b32_e32 v118, v50
	v_mov_b32_e32 v119, v50
	v_mov_b32_e32 v120, v50
	v_mov_b32_e32 v121, v50
	v_mov_b32_e32 v126, v50
	v_mov_b32_e32 v127, v50
	v_mov_b32_e32 v128, v50
	v_mov_b32_e32 v129, v50
	v_mov_b32_e32 v134, v50
	v_mov_b32_e32 v135, v50
	v_mov_b32_e32 v136, v50
	v_mov_b32_e32 v137, v50
	v_mov_b32_e32 v142, v50
	v_mov_b32_e32 v143, v50
	v_mov_b32_e32 v144, v50
	v_mov_b32_e32 v145, v50
	v_mov_b32_e32 v150, v50
	v_mov_b32_e32 v151, v50
	v_mov_b32_e32 v152, v50
	v_mov_b32_e32 v153, v50
	v_mov_b32_e32 v158, v50
	v_mov_b32_e32 v159, v50
	v_mov_b32_e32 v160, v50
	v_mov_b32_e32 v161, v50
	v_mov_b32_e32 v166, v50
	v_mov_b32_e32 v167, v50
	v_mov_b32_e32 v168, v50
	v_mov_b32_e32 v169, v50
	v_mov_b32_e32 v122, v50
	v_mov_b32_e32 v123, v50
	v_mov_b32_e32 v124, v50
	v_mov_b32_e32 v125, v50
	v_mov_b32_e32 v130, v50
	v_mov_b32_e32 v131, v50
	v_mov_b32_e32 v132, v50
	v_mov_b32_e32 v133, v50
	v_mov_b32_e32 v138, v50
	v_mov_b32_e32 v139, v50
	v_mov_b32_e32 v140, v50
	v_mov_b32_e32 v141, v50
	v_mov_b32_e32 v146, v50
	v_mov_b32_e32 v147, v50
	v_mov_b32_e32 v148, v50
	v_mov_b32_e32 v149, v50
	v_mov_b32_e32 v154, v50
	v_mov_b32_e32 v155, v50
	v_mov_b32_e32 v156, v50
	v_mov_b32_e32 v157, v50
	v_mov_b32_e32 v162, v50
	v_mov_b32_e32 v163, v50
	v_mov_b32_e32 v164, v50
	v_mov_b32_e32 v165, v50
	v_mov_b32_e32 v170, v50
	v_mov_b32_e32 v171, v50
	v_mov_b32_e32 v172, v50
	v_mov_b32_e32 v173, v50
	v_mov_b32_e32 v174, v50
	v_mov_b32_e32 v175, v50
	v_mov_b32_e32 v176, v50
	v_mov_b32_e32 v177, v50
	s_waitcnt vmcnt(0)
	.p2align 8

.LBB0_701:
	s_ashr_i32 s67, s66, 31
	s_lshl_b64 s[18:19], s[66:67], 21
	s_add_u32 s68, s6, s18
	s_addc_u32 s69, s7, s19
	s_and_b64 s[18:19], s[2:3], exec
	s_cselect_b32 s67, s69, s5
	s_cselect_b32 s82, s68, s4
	s_ashr_i32 s47, s46, 31
	s_lshl_b64 s[18:19], s[46:47], 21
	s_add_u32 s70, s64, s18
	s_addc_u32 s71, s65, s19
	s_and_b64 s[18:19], s[2:3], exec
	s_cselect_b32 s47, s71, s73
	s_cselect_b32 s83, s70, s72
	s_add_u32 s4, s4, 0x100080
	s_addc_u32 s5, s5, 0
	s_add_u32 s84, s72, 0x100
	v_mov_b32_e32 v2, 0
	s_addc_u32 s85, s73, 0
	s_mov_b32 s86, -2
	v_mov_b32_e32 v3, v2
	v_mov_b32_e32 v4, v2
	v_mov_b32_e32 v5, v2
	v_mov_b32_e32 v6, v2
	v_mov_b32_e32 v7, v2
	v_mov_b32_e32 v8, v2
	v_mov_b32_e32 v9, v2
	v_mov_b32_e32 v18, v2
	v_mov_b32_e32 v19, v2
	v_mov_b32_e32 v20, v2
	v_mov_b32_e32 v21, v2
	v_mov_b32_e32 v22, v2
	v_mov_b32_e32 v23, v2
	v_mov_b32_e32 v24, v2
	v_mov_b32_e32 v25, v2
	v_mov_b32_e32 v34, v2
	v_mov_b32_e32 v35, v2
	v_mov_b32_e32 v36, v2
	v_mov_b32_e32 v37, v2
	v_mov_b32_e32 v38, v2
	v_mov_b32_e32 v39, v2
	v_mov_b32_e32 v40, v2
	v_mov_b32_e32 v41, v2
	v_mov_b32_e32 v50, v2
	v_mov_b32_e32 v51, v2
	v_mov_b32_e32 v52, v2
	v_mov_b32_e32 v53, v2
	v_mov_b32_e32 v54, v2
	v_mov_b32_e32 v55, v2
	v_mov_b32_e32 v56, v2
	v_mov_b32_e32 v57, v2
	v_mov_b32_e32 v10, v2
	v_mov_b32_e32 v11, v2
	v_mov_b32_e32 v12, v2
	v_mov_b32_e32 v13, v2
	v_mov_b32_e32 v14, v2
	v_mov_b32_e32 v15, v2
	v_mov_b32_e32 v16, v2
	v_mov_b32_e32 v17, v2
	v_mov_b32_e32 v26, v2
	v_mov_b32_e32 v27, v2
	v_mov_b32_e32 v28, v2
	v_mov_b32_e32 v29, v2
	v_mov_b32_e32 v30, v2
	v_mov_b32_e32 v31, v2
	v_mov_b32_e32 v32, v2
	v_mov_b32_e32 v33, v2
	v_mov_b32_e32 v42, v2
	v_mov_b32_e32 v43, v2
	v_mov_b32_e32 v44, v2
	v_mov_b32_e32 v45, v2
	v_mov_b32_e32 v46, v2
	v_mov_b32_e32 v47, v2
	v_mov_b32_e32 v48, v2
	v_mov_b32_e32 v49, v2
	v_mov_b32_e32 v58, v2
	v_mov_b32_e32 v59, v2
	v_mov_b32_e32 v60, v2
	v_mov_b32_e32 v61, v2
	v_mov_b32_e32 v62, v2
	v_mov_b32_e32 v63, v2
	v_mov_b32_e32 v64, v2
	v_mov_b32_e32 v65, v2
	v_mov_b32_e32 v66, v2
	v_mov_b32_e32 v67, v2
	v_mov_b32_e32 v68, v2
	v_mov_b32_e32 v69, v2
	v_mov_b32_e32 v70, v2
	v_mov_b32_e32 v71, v2
	v_mov_b32_e32 v72, v2
	v_mov_b32_e32 v73, v2
	v_mov_b32_e32 v82, v2
	v_mov_b32_e32 v83, v2
	v_mov_b32_e32 v84, v2
	v_mov_b32_e32 v85, v2
	v_mov_b32_e32 v86, v2
	v_mov_b32_e32 v87, v2
	v_mov_b32_e32 v88, v2
	v_mov_b32_e32 v89, v2
	v_mov_b32_e32 v98, v2
	v_mov_b32_e32 v99, v2
	v_mov_b32_e32 v100, v2
	v_mov_b32_e32 v101, v2
	v_mov_b32_e32 v102, v2
	v_mov_b32_e32 v103, v2
	v_mov_b32_e32 v104, v2
	v_mov_b32_e32 v105, v2
	v_mov_b32_e32 v114, v2
	v_mov_b32_e32 v115, v2
	v_mov_b32_e32 v116, v2
	v_mov_b32_e32 v117, v2
	v_mov_b32_e32 v118, v2
	v_mov_b32_e32 v119, v2
	v_mov_b32_e32 v120, v2
	v_mov_b32_e32 v121, v2
	v_mov_b32_e32 v74, v2
	v_mov_b32_e32 v75, v2
	v_mov_b32_e32 v76, v2
	v_mov_b32_e32 v77, v2
	v_mov_b32_e32 v78, v2
	v_mov_b32_e32 v79, v2
	v_mov_b32_e32 v80, v2
	v_mov_b32_e32 v81, v2
	v_mov_b32_e32 v90, v2
	v_mov_b32_e32 v91, v2
	v_mov_b32_e32 v92, v2
	v_mov_b32_e32 v93, v2
	v_mov_b32_e32 v94, v2
	v_mov_b32_e32 v95, v2
	v_mov_b32_e32 v96, v2
	v_mov_b32_e32 v97, v2
	v_mov_b32_e32 v106, v2
	v_mov_b32_e32 v107, v2
	v_mov_b32_e32 v108, v2
	v_mov_b32_e32 v109, v2
	v_mov_b32_e32 v110, v2
	v_mov_b32_e32 v111, v2
	v_mov_b32_e32 v112, v2
	v_mov_b32_e32 v113, v2
	v_mov_b32_e32 v122, v2
	v_mov_b32_e32 v123, v2
	v_mov_b32_e32 v124, v2
	v_mov_b32_e32 v125, v2
	v_mov_b32_e32 v126, v2
	v_mov_b32_e32 v127, v2
	v_mov_b32_e32 v128, v2
	v_mov_b32_e32 v129, v2
	.p2align 8

.LBB0_910:
	s_ashr_i32 s43, s42, 31
	s_lshl_b64 s[18:19], s[42:43], 20
	s_add_u32 s44, s22, s18
	s_addc_u32 s45, s23, s19
	s_and_b64 s[18:19], s[6:7], exec
	s_cselect_b32 s13, s45, s67
	s_cselect_b32 s15, s44, s66
	s_ashr_i32 s41, s40, 31
	s_lshl_b64 s[18:19], s[40:41], 20
	s_add_u32 s46, s26, s18
	s_addc_u32 s47, s27, s19
	s_and_b64 s[18:19], s[6:7], exec
	s_cselect_b32 s24, s47, s69
	s_cselect_b32 s25, s46, s68
	s_add_u32 s66, s66, 0x80080
	s_addc_u32 s67, s67, 0
	s_add_u32 s41, s68, 0x100
	v_mov_b32_e32 v2, 0
	s_addc_u32 s43, s69, 0
	s_mov_b32 s60, -2
	v_mov_b32_e32 v3, v2
	v_mov_b32_e32 v4, v2
	v_mov_b32_e32 v5, v2
	v_mov_b32_e32 v10, v2
	v_mov_b32_e32 v11, v2
	v_mov_b32_e32 v12, v2
	v_mov_b32_e32 v13, v2
	v_mov_b32_e32 v18, v2
	v_mov_b32_e32 v19, v2
	v_mov_b32_e32 v20, v2
	v_mov_b32_e32 v21, v2
	v_mov_b32_e32 v26, v2
	v_mov_b32_e32 v27, v2
	v_mov_b32_e32 v28, v2
	v_mov_b32_e32 v29, v2
	v_mov_b32_e32 v34, v2
	v_mov_b32_e32 v35, v2
	v_mov_b32_e32 v36, v2
	v_mov_b32_e32 v37, v2
	v_mov_b32_e32 v42, v2
	v_mov_b32_e32 v43, v2
	v_mov_b32_e32 v44, v2
	v_mov_b32_e32 v45, v2
	v_mov_b32_e32 v54, v2
	v_mov_b32_e32 v55, v2
	v_mov_b32_e32 v56, v2
	v_mov_b32_e32 v57, v2
	v_mov_b32_e32 v66, v2
	v_mov_b32_e32 v67, v2
	v_mov_b32_e32 v68, v2
	v_mov_b32_e32 v69, v2
	v_mov_b32_e32 v6, v2
	v_mov_b32_e32 v7, v2
	v_mov_b32_e32 v8, v2
	v_mov_b32_e32 v9, v2
	v_mov_b32_e32 v14, v2
	v_mov_b32_e32 v15, v2
	v_mov_b32_e32 v16, v2
	v_mov_b32_e32 v17, v2
	v_mov_b32_e32 v22, v2
	v_mov_b32_e32 v23, v2
	v_mov_b32_e32 v24, v2
	v_mov_b32_e32 v25, v2
	v_mov_b32_e32 v30, v2
	v_mov_b32_e32 v31, v2
	v_mov_b32_e32 v32, v2
	v_mov_b32_e32 v33, v2
	v_mov_b32_e32 v38, v2
	v_mov_b32_e32 v39, v2
	v_mov_b32_e32 v40, v2
	v_mov_b32_e32 v41, v2
	v_mov_b32_e32 v46, v2
	v_mov_b32_e32 v47, v2
	v_mov_b32_e32 v48, v2
	v_mov_b32_e32 v49, v2
	v_mov_b32_e32 v58, v2
	v_mov_b32_e32 v59, v2
	v_mov_b32_e32 v60, v2
	v_mov_b32_e32 v61, v2
	v_mov_b32_e32 v70, v2
	v_mov_b32_e32 v71, v2
	v_mov_b32_e32 v72, v2
	v_mov_b32_e32 v73, v2
	v_mov_b32_e32 v74, v2
	v_mov_b32_e32 v75, v2
	v_mov_b32_e32 v76, v2
	v_mov_b32_e32 v77, v2
	v_mov_b32_e32 v82, v2
	v_mov_b32_e32 v83, v2
	v_mov_b32_e32 v84, v2
	v_mov_b32_e32 v85, v2
	v_mov_b32_e32 v90, v2
	v_mov_b32_e32 v91, v2
	v_mov_b32_e32 v92, v2
	v_mov_b32_e32 v93, v2
	v_mov_b32_e32 v98, v2
	v_mov_b32_e32 v99, v2
	v_mov_b32_e32 v100, v2
	v_mov_b32_e32 v101, v2
	v_mov_b32_e32 v106, v2
	v_mov_b32_e32 v107, v2
	v_mov_b32_e32 v108, v2
	v_mov_b32_e32 v109, v2
	v_mov_b32_e32 v114, v2
	v_mov_b32_e32 v115, v2
	v_mov_b32_e32 v116, v2
	v_mov_b32_e32 v117, v2
	v_mov_b32_e32 v122, v2
	v_mov_b32_e32 v123, v2
	v_mov_b32_e32 v124, v2
	v_mov_b32_e32 v125, v2
	v_mov_b32_e32 v130, v2
	v_mov_b32_e32 v131, v2
	v_mov_b32_e32 v132, v2
	v_mov_b32_e32 v133, v2
	v_mov_b32_e32 v78, v2
	v_mov_b32_e32 v79, v2
	v_mov_b32_e32 v80, v2
	v_mov_b32_e32 v81, v2
	v_mov_b32_e32 v86, v2
	v_mov_b32_e32 v87, v2
	v_mov_b32_e32 v88, v2
	v_mov_b32_e32 v89, v2
	v_mov_b32_e32 v94, v2
	v_mov_b32_e32 v95, v2
	v_mov_b32_e32 v96, v2
	v_mov_b32_e32 v97, v2
	v_mov_b32_e32 v102, v2
	v_mov_b32_e32 v103, v2
	v_mov_b32_e32 v104, v2
	v_mov_b32_e32 v105, v2
	v_mov_b32_e32 v110, v2
	v_mov_b32_e32 v111, v2
	v_mov_b32_e32 v112, v2
	v_mov_b32_e32 v113, v2
	v_mov_b32_e32 v118, v2
	v_mov_b32_e32 v119, v2
	v_mov_b32_e32 v120, v2
	v_mov_b32_e32 v121, v2
	v_mov_b32_e32 v126, v2
	v_mov_b32_e32 v127, v2
	v_mov_b32_e32 v128, v2
	v_mov_b32_e32 v129, v2
	v_mov_b32_e32 v134, v2
	v_mov_b32_e32 v135, v2
	v_mov_b32_e32 v136, v2
	v_mov_b32_e32 v137, v2
	.p2align 8

.LBB0_1081:
	s_add_u32 s40, s40, 0x158080
	s_addc_u32 s41, s41, 0
	s_add_u32 s73, s42, 0x100
	v_mov_b32_e32 v2, 0
	s_addc_u32 s74, s43, 0
	s_mov_b32 s75, -2
	v_mov_b32_e32 v3, v2
	v_mov_b32_e32 v4, v2
	v_mov_b32_e32 v5, v2
	v_mov_b32_e32 v6, v2
	v_mov_b32_e32 v7, v2
	v_mov_b32_e32 v8, v2
	v_mov_b32_e32 v9, v2
	v_mov_b32_e32 v14, v2
	v_mov_b32_e32 v15, v2
	v_mov_b32_e32 v16, v2
	v_mov_b32_e32 v17, v2
	v_mov_b32_e32 v22, v2
	v_mov_b32_e32 v23, v2
	v_mov_b32_e32 v24, v2
	v_mov_b32_e32 v25, v2
	v_mov_b32_e32 v30, v2
	v_mov_b32_e32 v31, v2
	v_mov_b32_e32 v32, v2
	v_mov_b32_e32 v33, v2
	v_mov_b32_e32 v38, v2
	v_mov_b32_e32 v39, v2
	v_mov_b32_e32 v40, v2
	v_mov_b32_e32 v41, v2
	v_mov_b32_e32 v46, v2
	v_mov_b32_e32 v47, v2
	v_mov_b32_e32 v48, v2
	v_mov_b32_e32 v49, v2
	v_mov_b32_e32 v54, v2
	v_mov_b32_e32 v55, v2
	v_mov_b32_e32 v56, v2
	v_mov_b32_e32 v57, v2
	v_mov_b32_e32 v10, v2
	v_mov_b32_e32 v11, v2
	v_mov_b32_e32 v12, v2
	v_mov_b32_e32 v13, v2
	v_mov_b32_e32 v18, v2
	v_mov_b32_e32 v19, v2
	v_mov_b32_e32 v20, v2
	v_mov_b32_e32 v21, v2
	v_mov_b32_e32 v26, v2
	v_mov_b32_e32 v27, v2
	v_mov_b32_e32 v28, v2
	v_mov_b32_e32 v29, v2
	v_mov_b32_e32 v34, v2
	v_mov_b32_e32 v35, v2
	v_mov_b32_e32 v36, v2
	v_mov_b32_e32 v37, v2
	v_mov_b32_e32 v42, v2
	v_mov_b32_e32 v43, v2
	v_mov_b32_e32 v44, v2
	v_mov_b32_e32 v45, v2
	v_mov_b32_e32 v50, v2
	v_mov_b32_e32 v51, v2
	v_mov_b32_e32 v52, v2
	v_mov_b32_e32 v53, v2
	v_mov_b32_e32 v58, v2
	v_mov_b32_e32 v59, v2
	v_mov_b32_e32 v60, v2
	v_mov_b32_e32 v61, v2
	v_mov_b32_e32 v62, v2
	v_mov_b32_e32 v63, v2
	v_mov_b32_e32 v64, v2
	v_mov_b32_e32 v65, v2
	v_mov_b32_e32 v66, v2
	v_mov_b32_e32 v67, v2
	v_mov_b32_e32 v68, v2
	v_mov_b32_e32 v69, v2
	v_mov_b32_e32 v70, v2
	v_mov_b32_e32 v71, v2
	v_mov_b32_e32 v72, v2
	v_mov_b32_e32 v73, v2
	v_mov_b32_e32 v82, v2
	v_mov_b32_e32 v83, v2
	v_mov_b32_e32 v84, v2
	v_mov_b32_e32 v85, v2
	v_mov_b32_e32 v86, v2
	v_mov_b32_e32 v87, v2
	v_mov_b32_e32 v88, v2
	v_mov_b32_e32 v89, v2
	v_mov_b32_e32 v98, v2
	v_mov_b32_e32 v99, v2
	v_mov_b32_e32 v100, v2
	v_mov_b32_e32 v101, v2
	v_mov_b32_e32 v102, v2
	v_mov_b32_e32 v103, v2
	v_mov_b32_e32 v104, v2
	v_mov_b32_e32 v105, v2
	v_mov_b32_e32 v110, v2
	v_mov_b32_e32 v111, v2
	v_mov_b32_e32 v112, v2
	v_mov_b32_e32 v113, v2
	v_mov_b32_e32 v118, v2
	v_mov_b32_e32 v119, v2
	v_mov_b32_e32 v120, v2
	v_mov_b32_e32 v121, v2
	v_mov_b32_e32 v74, v2
	v_mov_b32_e32 v75, v2
	v_mov_b32_e32 v76, v2
	v_mov_b32_e32 v77, v2
	v_mov_b32_e32 v78, v2
	v_mov_b32_e32 v79, v2
	v_mov_b32_e32 v80, v2
	v_mov_b32_e32 v81, v2
	v_mov_b32_e32 v90, v2
	v_mov_b32_e32 v91, v2
	v_mov_b32_e32 v92, v2
	v_mov_b32_e32 v93, v2
	v_mov_b32_e32 v94, v2
	v_mov_b32_e32 v95, v2
	v_mov_b32_e32 v96, v2
	v_mov_b32_e32 v97, v2
	v_mov_b32_e32 v106, v2
	v_mov_b32_e32 v107, v2
	v_mov_b32_e32 v108, v2
	v_mov_b32_e32 v109, v2
	v_mov_b32_e32 v114, v2
	v_mov_b32_e32 v115, v2
	v_mov_b32_e32 v116, v2
	v_mov_b32_e32 v117, v2
	v_mov_b32_e32 v122, v2
	v_mov_b32_e32 v123, v2
	v_mov_b32_e32 v124, v2
	v_mov_b32_e32 v125, v2
	v_mov_b32_e32 v126, v2
	v_mov_b32_e32 v127, v2
	v_mov_b32_e32 v128, v2
	v_mov_b32_e32 v129, v2
	.p2align 8
